# v35 + FFN-in first K-iteration peeled with C=0 MFMAs (no accumulator zeroing per unit)
# speedup vs baseline: 1.0009x; 1.0001x over previous
;     __device__ __forceinline__ void operator()(const f32x4 (&acc)[2][2][4][2], const Unit& u, int wr, int wc, int fr, int fq) const {
;     ...
;         { f32x4 pa[2][4], pb[2][4];
; #pragma unroll
;           for (int ai = 0; ai < 2; ++ai)
; #pragma unroll
;             for (int m = 0; m < 4; ++m) { const float* p_ = st2 + (size_t)(row0 + ai * HALF + m * 16) * 8; pa[ai][m] = *(const f32x4*)p_; pb[ai][m] = *(const f32x4*)(p_ + 4); }
;           __builtin_amdgcn_sched_barrier(0);
; #pragma unroll
;           for (int ai = 0; ai < 2; ++ai)
; #pragma unroll
;             for (int m = 0; m < 4; ++m) { const f32x4 t_ = pa[ai][m] + pb[ai][m]; rs8[ai][m] = __builtin_amdgcn_rsqf(((t_[0] + t_[1]) + (t_[2] + t_[3])) * (1.0f / (float)D) + 1e-6f); }
;           __builtin_amdgcn_sched_barrier(0); }
.Lmy_rsfill_done:
	s_or_b64 exec, exec, s[100:101]
	s_mov_b32 s100, s54
	s_waitcnt lgkmcnt(0)
	s_barrier
	v_readlane_b32 s19, v253, 54
	s_branch .LBB0_134
	s_nop 0
	s_nop 0
	s_nop 0
	s_nop 0
	s_nop 0
	s_nop 0
	s_nop 0
	s_nop 0
	s_nop 0
	s_nop 0
	s_nop 0
	s_nop 0
	s_nop 0
	s_nop 0
	s_nop 0
	s_nop 0
	s_nop 0
	s_nop 0
	s_nop 0
	s_nop 0
	s_nop 0
	s_nop 0
	s_nop 0
	s_nop 0
	s_nop 0
	s_nop 0
	s_nop 0
	s_nop 0
	s_nop 0
	s_nop 0
	s_nop 0
	s_nop 0
	s_nop 0
	s_nop 0
	s_nop 0
	s_nop 0

; #define PG8_STAGE(bufoff, gbase, voff) do { _Pragma("unroll") for (int _i = 0; _i < 2; ++_i) \
;         __builtin_amdgcn_global_load_lds((const unsigned*)((const char*)(gbase) + (voff)[_i]), (LAS unsigned*)(lds + (bufoff) + ldsw + _i * 8192), 16, 0, 0); } while (0)
; #define PG8_LDA(dst, b, h) do { _Pragma("unroll") for (int m = 0; m < 4; ++m) _Pragma("unroll") for (int k = 0; k < 2; ++k) dst[m][k] = *(const LAS bf16x8*)(lds + PG8_SA(b, h) + aoff + m * 2048 + k * 1024); } while (0)
; #define PG8_WAIT_V(n) asm volatile("s_waitcnt vmcnt(" #n ")" ::: "memory")
; template <class Epi, class Sched>
; __device__ __forceinline__ void gemm_phase(LAS unsigned char* lds, const Gemm g, const Sched& S, const Epi& E) {
;     ...
;         const bool has_next = S.next(ui + 1, nxt);
;         const char* nA = has_next ? (const char*)g.A + (size_t)nxt.pm * tstepA + (size_t)nxt.ka * 2 : cA; const char* nB = has_next ? (const char*)g.Bt + (size_t)nxt.pn * tstepB : cB;
;         for (int t = 0; t < nt; t += 2) {
;             const bool last = (t == nt - 2);
;             const char* a1 = cA + (size_t)(t + 1) * kstep;
;             const char* a2 = last ? nA : cA + (size_t)(t + 2) * kstep; const char* b2 = last ? nB : cB + (size_t)(t + 2) * kstep;
;             const char* a3 = a2 + kstep; const char* b3 = b2 + kstep;
;             if (last && has_next) S.a_ready(nxt);
;             PG8_LDB(B0, 0, 0); PG8_LDB(B1, 0, 1); PG8_SCHED; PG8_LDA(At, 0, 0); PG8_STAGE(PG8_SA(1, 1), a1 + hstepA, voffA);
;             PG8_WAIT_V(8); PG8_WAIT_L(0); PG8_BAR; PG8_MMA(0, 0, At, B0); PG8_MMA(0, 1, At, B1); PG8_BAR; PG8_SCHED;
;             PG8_LDA(At, 0, 1); PG8_STAGE(PG8_SB(0, 0), b2, voffB); PG8_STAGE(PG8_SB(0, 1), b2 + hstepB, voffB); PG8_STAGE(PG8_SA(0, 0), a2, voffA);
;             PG8_WAIT_V(8); PG8_WAIT_L(0); PG8_BAR; PG8_MMA(1, 0, At, B0); PG8_MMA(1, 1, At, B1); PG8_BAR; PG8_SCHED;
;             PG8_LDB(B0, 1, 0); PG8_LDB(B1, 1, 1); PG8_SCHED; PG8_LDA(At, 1, 0); PG8_STAGE(PG8_SA(0, 1), a2 + hstepA, voffA);
;             PG8_WAIT_V(8); PG8_WAIT_L(0); PG8_BAR; PG8_MMA(0, 0, At, B0); PG8_MMA(0, 1, At, B1); PG8_BAR; PG8_SCHED;
;             PG8_LDA(At, 1, 1); PG8_STAGE(PG8_SB(1, 0), b3, voffB); PG8_STAGE(PG8_SB(1, 1), b3 + hstepB, voffB); PG8_STAGE(PG8_SA(1, 0), a3, voffA);
;             PG8_WAIT_V(8); PG8_WAIT_L(0); PG8_BAR; PG8_MMA(1, 0, At, B0); PG8_MMA(1, 1, At, B1); PG8_BAR; PG8_SCHED;
.LBB0_136:
	s_ashr_i32 s21, s20, 31
	s_lshl_b64 s[22:23], s[20:21], 20
	s_add_u32 s22, s34, s22
	s_addc_u32 s23, s42, s23
	s_and_b64 s[24:25], s[38:39], exec
	s_cselect_b32 s21, s23, s27
	s_cselect_b32 s55, s22, s26
	s_ashr_i32 s19, s18, 31
	s_lshl_b64 s[24:25], s[18:19], 20
	s_add_u32 s24, s43, s24
	s_addc_u32 s25, s44, s25
	s_and_b64 s[40:41], s[38:39], exec
	s_cselect_b32 s19, s25, s29
	s_cselect_b32 s56, s24, s28
	s_add_u32 s26, s26, 0x80080
	s_addc_u32 s27, s27, 0
	s_add_u32 s57, s28, 0x100
	s_addc_u32 s58, s29, 0
	s_mov_b32 s59, -2
	s_add_u32 s28, s26, 0xfff80080
	s_addc_u32 s29, s27, -1
	s_add_i32 s60, 0, 0x10000
	s_cmp_eq_u32 s59, 28
	s_cselect_b32 s41, s21, s29
	s_cselect_b32 s40, s55, s28
	s_cselect_b32 s29, s19, s58
	s_cselect_b32 s28, s56, s57
	s_add_i32 s62, 0, 0x14000
	v_add_u32_e32 v154, s60, v159
	v_add_u32_e32 v174, s62, v159
	ds_read_b128 v[142:145], v154
	ds_read_b128 v[146:149], v154 offset:1024
	ds_read_b128 v[150:153], v154 offset:2048
	ds_read_b128 v[154:157], v154 offset:3072
	ds_read_b128 v[162:165], v174
	ds_read_b128 v[166:169], v174 offset:1024
	ds_read_b128 v[170:173], v174 offset:2048
	ds_read_b128 v[174:177], v174 offset:3072
	v_lshl_add_u64 v[224:225], s[26:27], 0, v[138:139]
	s_add_i32 m0, s46, 0xc000
	ds_read_b128 v[178:181], v161
	ds_read_b128 v[182:185], v161 offset:1024
	ds_read_b128 v[186:189], v161 offset:2048
	ds_read_b128 v[190:193], v161 offset:3072
	ds_read_b128 v[194:197], v161 offset:4096
	ds_read_b128 v[212:215], v161 offset:5120
	ds_read_b128 v[216:219], v161 offset:6144
	ds_read_b128 v[220:223], v161 offset:7168
	global_load_lds_dwordx4 v[224:225], off
	v_lshl_add_u64 v[224:225], s[26:27], 0, v[140:141]
	s_add_i32 m0, s46, 0xe000
	s_nop 0
	global_load_lds_dwordx4 v[224:225], off
	s_waitcnt vmcnt(8)
	s_waitcnt lgkmcnt(0)
	s_barrier
	s_waitcnt lgkmcnt(0)
	v_mfma_f32_16x16x32_bf16 v[130:133], v[142:145], v[178:181], 0
	v_mfma_f32_16x16x32_bf16 v[122:125], v[150:153], v[178:181], 0
	v_mfma_f32_16x16x32_bf16 v[114:117], v[142:145], v[186:189], 0
	v_mfma_f32_16x16x32_bf16 v[106:109], v[150:153], v[186:189], 0
	v_mfma_f32_16x16x32_bf16 v[98:101], v[142:145], v[194:197], 0
	v_mfma_f32_16x16x32_bf16 v[90:93], v[150:153], v[194:197], 0
	v_mfma_f32_16x16x32_bf16 v[82:85], v[142:145], v[216:219], 0
	v_mfma_f32_16x16x32_bf16 v[74:77], v[150:153], v[216:219], 0
	v_mfma_f32_16x16x32_bf16 v[130:133], v[146:149], v[182:185], v[130:133]
	v_mfma_f32_16x16x32_bf16 v[122:125], v[154:157], v[182:185], v[122:125]
	v_mfma_f32_16x16x32_bf16 v[114:117], v[146:149], v[190:193], v[114:117]
	v_mfma_f32_16x16x32_bf16 v[106:109], v[154:157], v[190:193], v[106:109]
	v_mfma_f32_16x16x32_bf16 v[98:101], v[146:149], v[212:215], v[98:101]
	v_mfma_f32_16x16x32_bf16 v[90:93], v[154:157], v[212:215], v[90:93]
	v_mfma_f32_16x16x32_bf16 v[82:85], v[146:149], v[220:223], v[82:85]
	v_mfma_f32_16x16x32_bf16 v[74:77], v[154:157], v[220:223], v[74:77]
	v_mfma_f32_16x16x32_bf16 v[126:129], v[162:165], v[178:181], 0
	v_mfma_f32_16x16x32_bf16 v[118:121], v[170:173], v[178:181], 0
	v_mfma_f32_16x16x32_bf16 v[110:113], v[162:165], v[186:189], 0
	v_mfma_f32_16x16x32_bf16 v[102:105], v[170:173], v[186:189], 0
	v_mfma_f32_16x16x32_bf16 v[94:97], v[162:165], v[194:197], 0
	v_mfma_f32_16x16x32_bf16 v[86:89], v[170:173], v[194:197], 0
	v_mfma_f32_16x16x32_bf16 v[78:81], v[162:165], v[216:219], 0
	v_mfma_f32_16x16x32_bf16 v[70:73], v[170:173], v[216:219], 0
	v_mfma_f32_16x16x32_bf16 v[126:129], v[166:169], v[182:185], v[126:129]
	v_mfma_f32_16x16x32_bf16 v[118:121], v[174:177], v[182:185], v[118:121]
	v_mfma_f32_16x16x32_bf16 v[110:113], v[166:169], v[190:193], v[110:113]
	v_mfma_f32_16x16x32_bf16 v[102:105], v[174:177], v[190:193], v[102:105]
	v_mfma_f32_16x16x32_bf16 v[94:97], v[166:169], v[212:215], v[94:97]
	v_mfma_f32_16x16x32_bf16 v[86:89], v[174:177], v[212:215], v[86:89]
	v_mfma_f32_16x16x32_bf16 v[78:81], v[166:169], v[220:223], v[78:81]
	v_mfma_f32_16x16x32_bf16 v[70:73], v[174:177], v[220:223], v[70:73]
	s_barrier
	s_add_i32 s60, s60, s45
	v_lshl_add_u64 v[224:225], s[28:29], 0, v[4:5]
	s_mov_b32 m0, s60
	ds_read_b128 v[178:181], v161 offset:16384
	ds_read_b128 v[182:185], v161 offset:17408
	ds_read_b128 v[186:189], v161 offset:18432
	ds_read_b128 v[190:193], v161 offset:19456
	ds_read_b128 v[194:197], v161 offset:20480
	ds_read_b128 v[212:215], v161 offset:21504
	ds_read_b128 v[216:219], v161 offset:22528
	ds_read_b128 v[220:223], v161 offset:23552
	global_load_lds_dwordx4 v[224:225], off
	s_add_i32 m0, s60, 0x2000
	s_add_u32 s60, s28, 0x80000
	v_lshl_add_u64 v[226:227], s[28:29], 0, v[2:3]
	s_addc_u32 s61, s29, 0
	s_add_i32 s62, s62, s45
	global_load_lds_dwordx4 v[226:227], off
	v_lshl_add_u64 v[228:229], s[60:61], 0, v[4:5]
	s_mov_b32 m0, s62
	v_lshl_add_u64 v[230:231], s[40:41], 0, v[134:135]
	global_load_lds_dwordx4 v[228:229], off
	v_lshl_add_u64 v[228:229], s[60:61], 0, v[2:3]
	s_add_i32 m0, s62, 0x2000
	s_nop 0
	global_load_lds_dwordx4 v[228:229], off
	v_lshl_add_u64 v[228:229], s[40:41], 0, v[136:137]
	s_mov_b32 m0, s46
	s_nop 0
	global_load_lds_dwordx4 v[228:229], off
	s_mov_b32 m0, s47
	s_nop 0
	global_load_lds_dwordx4 v[230:231], off
	s_waitcnt vmcnt(8)
	s_waitcnt lgkmcnt(0)
	s_barrier
; #define PG8_STAGE(bufoff, gbase, voff) do { _Pragma("unroll") for (int _i = 0; _i < 2; ++_i) \
;         __builtin_amdgcn_global_load_lds((const unsigned*)((const char*)(gbase) + (voff)[_i]), (LAS unsigned*)(lds + (bufoff) + ldsw + _i * 8192), 16, 0, 0); } while (0)
; #define PG8_LDA(dst, b, h) do { _Pragma("unroll") for (int m = 0; m < 4; ++m) _Pragma("unroll") for (int k = 0; k < 2; ++k) dst[m][k] = *(const LAS bf16x8*)(lds + PG8_SA(b, h) + aoff + m * 2048 + k * 1024); } while (0)
; #define PG8_LDB(dst, b, h) do { _Pragma("unroll") for (int n = 0; n < 2; ++n) _Pragma("unroll") for (int k = 0; k < 2; ++k) dst[n][k] = *(const LAS bf16x8*)(lds + PG8_SB(b, h) + boff + n * 2048 + k * 1024); } while (0)
; #define PG8_MMA(ai, bj, At, Bt) do { __builtin_amdgcn_s_setprio(1); _Pragma("unroll") for (int m = 0; m < 4; ++m) _Pragma("unroll") for (int n = 0; n < 2; ++n) _Pragma("unroll") for (int k = 0; k < 2; ++k) \
;         acc[ai][bj][m][n] = __builtin_amdgcn_mfma_f32_16x16x32_bf16(Bt[n][k], At[m][k], acc[ai][bj][m][n], 0, 0, 0); __builtin_amdgcn_s_setprio(0); } while (0)
; #define PG8_WAIT_V(n) asm volatile("s_waitcnt vmcnt(" #n ")" ::: "memory")
; #define PG8_BAR __builtin_amdgcn_s_barrier()
; template <class Epi, class Sched>
; __device__ __forceinline__ void gemm_phase(LAS unsigned char* lds, const Gemm g, const Sched& S, const Epi& E) {
;     ...
;             PG8_LDB(B0, 0, 0); PG8_LDB(B1, 0, 1); PG8_SCHED; PG8_LDA(At, 0, 0); PG8_STAGE(PG8_SA(1, 1), a1 + hstepA, voffA);
;             PG8_WAIT_V(8); PG8_WAIT_L(0); PG8_BAR; PG8_MMA(0, 0, At, B0); PG8_MMA(0, 1, At, B1); PG8_BAR; PG8_SCHED;
;             PG8_LDA(At, 0, 1); PG8_STAGE(PG8_SB(0, 0), b2, voffB); PG8_STAGE(PG8_SB(0, 1), b2 + hstepB, voffB); PG8_STAGE(PG8_SA(0, 0), a2, voffA);
;             PG8_WAIT_V(8); PG8_WAIT_L(0); PG8_BAR; PG8_MMA(1, 0, At, B0); PG8_MMA(1, 1, At, B1); PG8_BAR; PG8_SCHED;
;             PG8_LDB(B0, 1, 0); PG8_LDB(B1, 1, 1); PG8_SCHED; PG8_LDA(At, 1, 0); PG8_STAGE(PG8_SA(0, 1), a2 + hstepA, voffA);
;             PG8_WAIT_V(8); PG8_WAIT_L(0); PG8_BAR; PG8_MMA(0, 0, At, B0); PG8_MMA(0, 1, At, B1); PG8_BAR; PG8_SCHED;
;             PG8_LDA(At, 1, 1); PG8_STAGE(PG8_SB(1, 0), b3, voffB); PG8_STAGE(PG8_SB(1, 1), b3 + hstepB, voffB); PG8_STAGE(PG8_SA(1, 0), a3, voffA);
;             PG8_WAIT_V(8); PG8_WAIT_L(0); PG8_BAR; PG8_MMA(1, 0, At, B0); PG8_MMA(1, 1, At, B1); PG8_BAR; PG8_SCHED;
	s_waitcnt lgkmcnt(0)
	v_mfma_f32_16x16x32_bf16 v[66:69], v[142:145], v[178:181], 0
	v_mfma_f32_16x16x32_bf16 v[58:61], v[150:153], v[178:181], 0
	v_mfma_f32_16x16x32_bf16 v[50:53], v[142:145], v[186:189], 0
	v_mfma_f32_16x16x32_bf16 v[42:45], v[150:153], v[186:189], 0
	v_mfma_f32_16x16x32_bf16 v[34:37], v[142:145], v[194:197], 0
	v_mfma_f32_16x16x32_bf16 v[26:29], v[150:153], v[194:197], 0
	v_mfma_f32_16x16x32_bf16 v[18:21], v[142:145], v[216:219], 0
	v_mfma_f32_16x16x32_bf16 v[10:13], v[150:153], v[216:219], 0
	v_mfma_f32_16x16x32_bf16 v[66:69], v[146:149], v[182:185], v[66:69]
	v_mfma_f32_16x16x32_bf16 v[58:61], v[154:157], v[182:185], v[58:61]
	v_mfma_f32_16x16x32_bf16 v[50:53], v[146:149], v[190:193], v[50:53]
	v_mfma_f32_16x16x32_bf16 v[42:45], v[154:157], v[190:193], v[42:45]
	v_mfma_f32_16x16x32_bf16 v[34:37], v[146:149], v[212:215], v[34:37]
	v_mfma_f32_16x16x32_bf16 v[26:29], v[154:157], v[212:215], v[26:29]
	v_mfma_f32_16x16x32_bf16 v[18:21], v[146:149], v[220:223], v[18:21]
	v_mfma_f32_16x16x32_bf16 v[10:13], v[154:157], v[220:223], v[10:13]
	v_mfma_f32_16x16x32_bf16 v[62:65], v[162:165], v[178:181], 0
	v_mfma_f32_16x16x32_bf16 v[54:57], v[170:173], v[178:181], 0
	v_mfma_f32_16x16x32_bf16 v[46:49], v[162:165], v[186:189], 0
	v_mfma_f32_16x16x32_bf16 v[38:41], v[170:173], v[186:189], 0
	v_mfma_f32_16x16x32_bf16 v[30:33], v[162:165], v[194:197], 0
	v_mfma_f32_16x16x32_bf16 v[22:25], v[170:173], v[194:197], 0
	v_mfma_f32_16x16x32_bf16 v[14:17], v[162:165], v[216:219], 0
	v_mfma_f32_16x16x32_bf16 v[6:9], v[170:173], v[216:219], 0
	v_mfma_f32_16x16x32_bf16 v[62:65], v[166:169], v[182:185], v[62:65]
	v_mfma_f32_16x16x32_bf16 v[54:57], v[174:177], v[182:185], v[54:57]
	v_mfma_f32_16x16x32_bf16 v[46:49], v[166:169], v[190:193], v[46:49]
	v_mfma_f32_16x16x32_bf16 v[38:41], v[174:177], v[190:193], v[38:41]
	v_mfma_f32_16x16x32_bf16 v[30:33], v[166:169], v[212:215], v[30:33]
	v_mfma_f32_16x16x32_bf16 v[22:25], v[174:177], v[212:215], v[22:25]
	v_mfma_f32_16x16x32_bf16 v[14:17], v[166:169], v[220:223], v[14:17]
	v_mfma_f32_16x16x32_bf16 v[6:9], v[174:177], v[220:223], v[6:9]
	s_barrier
	s_add_i32 s60, 0, 0x18000
	s_add_i32 s61, 0, 0x1c000
	v_add_u32_e32 v154, s60, v159
	v_add_u32_e32 v174, s61, v159
	ds_read_b128 v[142:145], v154
	ds_read_b128 v[146:149], v154 offset:1024
	ds_read_b128 v[150:153], v154 offset:2048
	ds_read_b128 v[154:157], v154 offset:3072
	ds_read_b128 v[162:165], v174
	ds_read_b128 v[166:169], v174 offset:1024
	ds_read_b128 v[170:173], v174 offset:2048
	ds_read_b128 v[174:177], v174 offset:3072
	s_add_u32 s40, s40, 0x80000
	s_addc_u32 s41, s41, 0
	s_mov_b32 m0, s48
	v_lshl_add_u64 v[236:237], s[40:41], 0, v[136:137]
	ds_read_b128 v[178:181], v161 offset:32768
	ds_read_b128 v[182:185], v161 offset:33792
	ds_read_b128 v[186:189], v161 offset:34816
	ds_read_b128 v[190:193], v161 offset:35840
	ds_read_b128 v[194:197], v161 offset:36864
	ds_read_b128 v[212:215], v161 offset:37888
	ds_read_b128 v[216:219], v161 offset:38912
	ds_read_b128 v[220:223], v161 offset:39936
	global_load_lds_dwordx4 v[236:237], off
	v_lshl_add_u64 v[236:237], s[40:41], 0, v[134:135]
	s_mov_b32 m0, s49
	s_nop 0
	global_load_lds_dwordx4 v[236:237], off
	s_waitcnt vmcnt(8)
	s_waitcnt lgkmcnt(0)
	s_barrier
	s_waitcnt lgkmcnt(0)
	v_mfma_f32_16x16x32_bf16 v[130:133], v[142:145], v[178:181], v[130:133]
	v_mfma_f32_16x16x32_bf16 v[122:125], v[150:153], v[178:181], v[122:125]
	v_mfma_f32_16x16x32_bf16 v[114:117], v[142:145], v[186:189], v[114:117]
	v_mfma_f32_16x16x32_bf16 v[106:109], v[150:153], v[186:189], v[106:109]
	v_mfma_f32_16x16x32_bf16 v[98:101], v[142:145], v[194:197], v[98:101]
	v_mfma_f32_16x16x32_bf16 v[90:93], v[150:153], v[194:197], v[90:93]
	v_mfma_f32_16x16x32_bf16 v[82:85], v[142:145], v[216:219], v[82:85]
	v_mfma_f32_16x16x32_bf16 v[74:77], v[150:153], v[216:219], v[74:77]
	v_mfma_f32_16x16x32_bf16 v[130:133], v[146:149], v[182:185], v[130:133]
	v_mfma_f32_16x16x32_bf16 v[122:125], v[154:157], v[182:185], v[122:125]
	v_mfma_f32_16x16x32_bf16 v[114:117], v[146:149], v[190:193], v[114:117]
	v_mfma_f32_16x16x32_bf16 v[106:109], v[154:157], v[190:193], v[106:109]
	v_mfma_f32_16x16x32_bf16 v[98:101], v[146:149], v[212:215], v[98:101]
	v_mfma_f32_16x16x32_bf16 v[90:93], v[154:157], v[212:215], v[90:93]
	v_mfma_f32_16x16x32_bf16 v[82:85], v[146:149], v[220:223], v[82:85]
	v_mfma_f32_16x16x32_bf16 v[74:77], v[154:157], v[220:223], v[74:77]
	v_mfma_f32_16x16x32_bf16 v[126:129], v[162:165], v[178:181], v[126:129]
	v_mfma_f32_16x16x32_bf16 v[118:121], v[170:173], v[178:181], v[118:121]
	v_mfma_f32_16x16x32_bf16 v[110:113], v[162:165], v[186:189], v[110:113]
	v_mfma_f32_16x16x32_bf16 v[102:105], v[170:173], v[186:189], v[102:105]
	v_mfma_f32_16x16x32_bf16 v[94:97], v[162:165], v[194:197], v[94:97]
	v_mfma_f32_16x16x32_bf16 v[86:89], v[170:173], v[194:197], v[86:89]
	v_mfma_f32_16x16x32_bf16 v[78:81], v[162:165], v[216:219], v[78:81]
	v_mfma_f32_16x16x32_bf16 v[70:73], v[170:173], v[216:219], v[70:73]
	v_mfma_f32_16x16x32_bf16 v[126:129], v[166:169], v[182:185], v[126:129]
	v_mfma_f32_16x16x32_bf16 v[118:121], v[174:177], v[182:185], v[118:121]
	v_mfma_f32_16x16x32_bf16 v[110:113], v[166:169], v[190:193], v[110:113]
	v_mfma_f32_16x16x32_bf16 v[102:105], v[174:177], v[190:193], v[102:105]
	v_mfma_f32_16x16x32_bf16 v[94:97], v[166:169], v[212:215], v[94:97]
	v_mfma_f32_16x16x32_bf16 v[86:89], v[174:177], v[212:215], v[86:89]
	v_mfma_f32_16x16x32_bf16 v[78:81], v[166:169], v[220:223], v[78:81]
	v_mfma_f32_16x16x32_bf16 v[70:73], v[174:177], v[220:223], v[70:73]
	s_barrier
; #define PG8_STAGE(bufoff, gbase, voff) do { _Pragma("unroll") for (int _i = 0; _i < 2; ++_i) \
;         __builtin_amdgcn_global_load_lds((const unsigned*)((const char*)(gbase) + (voff)[_i]), (LAS unsigned*)(lds + (bufoff) + ldsw + _i * 8192), 16, 0, 0); } while (0)
; #define PG8_LDA(dst, b, h) do { _Pragma("unroll") for (int m = 0; m < 4; ++m) _Pragma("unroll") for (int k = 0; k < 2; ++k) dst[m][k] = *(const LAS bf16x8*)(lds + PG8_SA(b, h) + aoff + m * 2048 + k * 1024); } while (0)
; #define PG8_LDB(dst, b, h) do { _Pragma("unroll") for (int n = 0; n < 2; ++n) _Pragma("unroll") for (int k = 0; k < 2; ++k) dst[n][k] = *(const LAS bf16x8*)(lds + PG8_SB(b, h) + boff + n * 2048 + k * 1024); } while (0)
; #define PG8_MMA(ai, bj, At, Bt) do { __builtin_amdgcn_s_setprio(1); _Pragma("unroll") for (int m = 0; m < 4; ++m) _Pragma("unroll") for (int n = 0; n < 2; ++n) _Pragma("unroll") for (int k = 0; k < 2; ++k) \
;         acc[ai][bj][m][n] = __builtin_amdgcn_mfma_f32_16x16x32_bf16(Bt[n][k], At[m][k], acc[ai][bj][m][n], 0, 0, 0); __builtin_amdgcn_s_setprio(0); } while (0)
; #define PG8_WAIT_V(n) asm volatile("s_waitcnt vmcnt(" #n ")" ::: "memory")
; #define PG8_WAIT_L(n) asm volatile("s_waitcnt lgkmcnt(" #n ")" ::: "memory")
; #define PG8_BAR __builtin_amdgcn_s_barrier()
; #define PG8_SCHED __builtin_amdgcn_sched_barrier(0)
; template <class Epi, class Sched>
; __device__ __forceinline__ void gemm_phase(LAS unsigned char* lds, const Gemm g, const Sched& S, const Epi& E) {
;     ...
;             PG8_LDB(B0, 1, 0); PG8_LDB(B1, 1, 1); PG8_SCHED; PG8_LDA(At, 1, 0); PG8_STAGE(PG8_SA(0, 1), a2 + hstepA, voffA);
;             PG8_WAIT_V(8); PG8_WAIT_L(0); PG8_BAR; PG8_MMA(0, 0, At, B0); PG8_MMA(0, 1, At, B1); PG8_BAR; PG8_SCHED;
;             PG8_LDA(At, 1, 1); PG8_STAGE(PG8_SB(1, 0), b3, voffB); PG8_STAGE(PG8_SB(1, 1), b3 + hstepB, voffB); PG8_STAGE(PG8_SA(1, 0), a3, voffA);
;             PG8_WAIT_V(8); PG8_WAIT_L(0); PG8_BAR; PG8_MMA(1, 0, At, B0); PG8_MMA(1, 1, At, B1); PG8_BAR; PG8_SCHED;
;         }
	s_add_i32 s40, s60, s45
	v_lshl_add_u64 v[224:225], v[224:225], 0, s[36:37]
	s_mov_b32 m0, s40
	ds_read_b128 v[178:181], v161 offset:49152
	ds_read_b128 v[182:185], v161 offset:50176
	ds_read_b128 v[186:189], v161 offset:51200
	ds_read_b128 v[190:193], v161 offset:52224
	ds_read_b128 v[194:197], v161 offset:53248
	ds_read_b128 v[212:215], v161 offset:54272
	ds_read_b128 v[216:219], v161 offset:55296
	ds_read_b128 v[220:223], v161 offset:56320
	global_load_lds_dwordx4 v[224:225], off
	s_add_i32 m0, s40, 0x2000
	s_add_u32 s28, s28, 0x80080
	v_lshl_add_u64 v[224:225], v[226:227], 0, s[36:37]
	s_addc_u32 s29, s29, 0
	s_add_i32 s40, s61, s45
	global_load_lds_dwordx4 v[224:225], off
	v_lshl_add_u64 v[224:225], s[28:29], 0, v[4:5]
	s_mov_b32 m0, s40
	s_nop 0
	global_load_lds_dwordx4 v[224:225], off
	v_lshl_add_u64 v[224:225], s[28:29], 0, v[2:3]
	s_add_i32 m0, s40, 0x2000
	s_nop 0
	global_load_lds_dwordx4 v[224:225], off
	v_lshl_add_u64 v[224:225], v[228:229], 0, s[36:37]
	s_mov_b32 m0, s50
	s_nop 0
	global_load_lds_dwordx4 v[224:225], off
	v_lshl_add_u64 v[224:225], v[230:231], 0, s[36:37]
	s_mov_b32 m0, s51
	s_nop 0
	global_load_lds_dwordx4 v[224:225], off
	s_waitcnt vmcnt(8)
	s_waitcnt lgkmcnt(0)
	s_barrier
	s_waitcnt lgkmcnt(0)
	v_mfma_f32_16x16x32_bf16 v[66:69], v[142:145], v[178:181], v[66:69]
	v_mfma_f32_16x16x32_bf16 v[58:61], v[150:153], v[178:181], v[58:61]
	v_mfma_f32_16x16x32_bf16 v[50:53], v[142:145], v[186:189], v[50:53]
	v_mfma_f32_16x16x32_bf16 v[42:45], v[150:153], v[186:189], v[42:45]
	v_mfma_f32_16x16x32_bf16 v[34:37], v[142:145], v[194:197], v[34:37]
	v_mfma_f32_16x16x32_bf16 v[26:29], v[150:153], v[194:197], v[26:29]
	v_mfma_f32_16x16x32_bf16 v[18:21], v[142:145], v[216:219], v[18:21]
	v_mfma_f32_16x16x32_bf16 v[10:13], v[150:153], v[216:219], v[10:13]
	v_mfma_f32_16x16x32_bf16 v[66:69], v[146:149], v[182:185], v[66:69]
	v_mfma_f32_16x16x32_bf16 v[58:61], v[154:157], v[182:185], v[58:61]
	v_mfma_f32_16x16x32_bf16 v[50:53], v[146:149], v[190:193], v[50:53]
	v_mfma_f32_16x16x32_bf16 v[42:45], v[154:157], v[190:193], v[42:45]
	v_mfma_f32_16x16x32_bf16 v[34:37], v[146:149], v[212:215], v[34:37]
	v_mfma_f32_16x16x32_bf16 v[26:29], v[154:157], v[212:215], v[26:29]
	v_mfma_f32_16x16x32_bf16 v[18:21], v[146:149], v[220:223], v[18:21]
	v_mfma_f32_16x16x32_bf16 v[10:13], v[154:157], v[220:223], v[10:13]
	v_mfma_f32_16x16x32_bf16 v[62:65], v[162:165], v[178:181], v[62:65]
	v_mfma_f32_16x16x32_bf16 v[54:57], v[170:173], v[178:181], v[54:57]
	v_mfma_f32_16x16x32_bf16 v[46:49], v[162:165], v[186:189], v[46:49]
	v_mfma_f32_16x16x32_bf16 v[38:41], v[170:173], v[186:189], v[38:41]
	v_mfma_f32_16x16x32_bf16 v[30:33], v[162:165], v[194:197], v[30:33]
	v_mfma_f32_16x16x32_bf16 v[22:25], v[170:173], v[194:197], v[22:25]
	v_mfma_f32_16x16x32_bf16 v[14:17], v[162:165], v[216:219], v[14:17]
	v_mfma_f32_16x16x32_bf16 v[6:9], v[170:173], v[216:219], v[6:9]
	v_mfma_f32_16x16x32_bf16 v[62:65], v[166:169], v[182:185], v[62:65]
	v_mfma_f32_16x16x32_bf16 v[54:57], v[174:177], v[182:185], v[54:57]
	v_mfma_f32_16x16x32_bf16 v[46:49], v[166:169], v[190:193], v[46:49]
	v_mfma_f32_16x16x32_bf16 v[38:41], v[174:177], v[190:193], v[38:41]
	v_mfma_f32_16x16x32_bf16 v[30:33], v[166:169], v[212:215], v[30:33]
	v_mfma_f32_16x16x32_bf16 v[22:25], v[174:177], v[212:215], v[22:25]
	v_mfma_f32_16x16x32_bf16 v[14:17], v[166:169], v[220:223], v[14:17]
	v_mfma_f32_16x16x32_bf16 v[6:9], v[174:177], v[220:223], v[6:9]
	s_barrier
	s_add_i32 s59, s59, 2
	s_add_u32 s26, s26, 0x100
	s_addc_u32 s27, s27, 0
	s_add_u32 s57, s57, 0x100
	s_addc_u32 s58, s58, 0
	s_cmp_gt_u32 s59, 29
